# v175 plus attention cross-half row max via v_permlane32_swap instead of the ds_bpermute LDS round trip (byte-size neutral)
# baseline (speedup 1.0000x reference)
; __device__ __forceinline__ float fast_exp2(float x) { return __builtin_amdgcn_exp2f(x); }
; __device__ __forceinline__ void attn_block(KP p, LAS unsigned char* lds, int bh, int q0) {
;     ...
;             float mx = s0[0];
; #pragma unroll
;             for (int i = 1; i < 16; ++i) mx = fmaxf(mx, s0[i]);
; #pragma unroll
;             for (int i = 0; i < 16; ++i) mx = fmaxf(mx, s1[i]);
;             mx = fmaxf(mx, __shfl_xor(mx, 32));
;             if (__builtin_amdgcn_ballot_w64(mx > mrun) != 0ull) {
;                 const float mnew = fmaxf(mrun, mx), alpha = fast_exp2(mrun - mnew);
;                 lrun *= alpha; mrun = mnew; o0 = o0 * alpha; o1 = o1 * alpha;
;             }
.LBB0_249:
	s_nop 3
	v_max_f32_e32 v0, v51, v51
	v_max_f32_e32 v162, v50, v50
	v_max_f32_e32 v0, v162, v0
	v_max3_f32 v0, v0, v52, v53
	v_max3_f32 v0, v0, v54, v55
	v_max3_f32 v0, v0, v56, v57
	v_max3_f32 v0, v0, v58, v59
	v_max3_f32 v0, v0, v60, v61
	v_max3_f32 v0, v0, v62, v63
	v_max3_f32 v0, v0, v64, v65
	v_max3_f32 v0, v0, v34, v35
	v_max3_f32 v0, v0, v36, v37
	v_max3_f32 v0, v0, v38, v39
	v_max3_f32 v0, v0, v40, v41
	v_and_b32_e32 v163, 64, v193
	v_max3_f32 v0, v0, v42, v43
	v_xor_b32_e32 v162, 32, v193
	v_add_u32_e32 v163, 64, v163
	v_max3_f32 v0, v0, v44, v45
	v_cmp_lt_i32_e32 vcc, v162, v163
	v_max3_f32 v0, v0, v46, v47
	v_max3_f32 v0, v0, v48, v49
	v_cndmask_b32_e32 v162, v193, v162, vcc
	v_lshlrev_b32_e32 v162, 2, v162
	v_mov_b32_e32 v162, v0
	s_nop 1
	v_permlane32_swap_b32_e32 v162, v0
	s_waitcnt lgkmcnt(0)
	v_max_f32_e32 v0, v0, v162
	v_cmp_gt_f32_e32 vcc, v0, v175
	s_cbranch_vccz .LBB0_251
	v_max_f32_e32 v0, v0, v0
	v_max_f32_e32 v162, v175, v175
	v_max_f32_e32 v162, v162, v0
	v_sub_f32_e32 v0, v175, v162
	v_exp_f32_e32 v0, v0
	v_mov_b32_e32 v175, v162
	v_mul_f32_e32 v174, v174, v0
	v_pk_mul_f32 v[32:33], v[32:33], v[0:1] op_sel_hi:[1,0]
	v_pk_mul_f32 v[30:31], v[30:31], v[0:1] op_sel_hi:[1,0]
	v_pk_mul_f32 v[28:29], v[28:29], v[0:1] op_sel_hi:[1,0]
	v_pk_mul_f32 v[26:27], v[26:27], v[0:1] op_sel_hi:[1,0]
	v_pk_mul_f32 v[24:25], v[24:25], v[0:1] op_sel_hi:[1,0]
	v_pk_mul_f32 v[22:23], v[22:23], v[0:1] op_sel_hi:[1,0]
	v_pk_mul_f32 v[20:21], v[20:21], v[0:1] op_sel_hi:[1,0]
	v_pk_mul_f32 v[18:19], v[18:19], v[0:1] op_sel_hi:[1,0]
	v_pk_mul_f32 v[16:17], v[16:17], v[0:1] op_sel_hi:[1,0]
	v_pk_mul_f32 v[14:15], v[14:15], v[0:1] op_sel_hi:[1,0]
	v_pk_mul_f32 v[12:13], v[12:13], v[0:1] op_sel_hi:[1,0]
	v_pk_mul_f32 v[10:11], v[10:11], v[0:1] op_sel_hi:[1,0]
	v_pk_mul_f32 v[8:9], v[8:9], v[0:1] op_sel_hi:[1,0]
	v_pk_mul_f32 v[6:7], v[6:7], v[0:1] op_sel_hi:[1,0]
	v_pk_mul_f32 v[4:5], v[4:5], v[0:1] op_sel_hi:[1,0]
	v_pk_mul_f32 v[2:3], v[2:3], v[0:1] op_sel_hi:[1,0]

; __device__ __forceinline__ float fast_exp2(float x) { return __builtin_amdgcn_exp2f(x); }
; __device__ __forceinline__ void attn_block(KP p, LAS unsigned char* lds, int bh, int q0) {
;     ...
;             float mx = s0[0];
; #pragma unroll
;             for (int i = 1; i < 16; ++i) mx = fmaxf(mx, s0[i]);
; #pragma unroll
;             for (int i = 0; i < 16; ++i) mx = fmaxf(mx, s1[i]);
;             mx = fmaxf(mx, __shfl_xor(mx, 32));
;             if (__builtin_amdgcn_ballot_w64(mx > mrun) != 0ull) {
;                 const float mnew = fmaxf(mrun, mx), alpha = fast_exp2(mrun - mnew);
;                 lrun *= alpha; mrun = mnew; o0 = o0 * alpha; o1 = o1 * alpha;
;             }
.LBB0_255:
	s_nop 3
	v_max_f32_e32 v0, v51, v51
	v_max_f32_e32 v162, v50, v50
	v_max_f32_e32 v0, v162, v0
	v_max3_f32 v0, v0, v52, v53
	v_max3_f32 v0, v0, v54, v55
	v_max3_f32 v0, v0, v56, v57
	v_max3_f32 v0, v0, v58, v59
	v_max3_f32 v0, v0, v60, v61
	v_max3_f32 v0, v0, v62, v63
	v_max3_f32 v0, v0, v64, v65
	v_max3_f32 v0, v0, v34, v35
	v_max3_f32 v0, v0, v36, v37
	v_max3_f32 v0, v0, v38, v39
	v_max3_f32 v0, v0, v40, v41
	v_and_b32_e32 v163, 64, v193
	v_max3_f32 v0, v0, v42, v43
	v_xor_b32_e32 v162, 32, v193
	v_add_u32_e32 v163, 64, v163
	v_max3_f32 v0, v0, v44, v45
	v_cmp_lt_i32_e32 vcc, v162, v163
	v_max3_f32 v0, v0, v46, v47
	v_max3_f32 v0, v0, v48, v49
	v_cndmask_b32_e32 v162, v193, v162, vcc
	v_lshlrev_b32_e32 v162, 2, v162
	v_mov_b32_e32 v162, v0
	s_nop 1
	v_permlane32_swap_b32_e32 v162, v0
	s_waitcnt lgkmcnt(0)
	v_max_f32_e32 v0, v0, v162
	v_cmp_gt_f32_e32 vcc, v0, v175
	s_cbranch_vccz .LBB0_242
	v_max_f32_e32 v0, v0, v0
	v_max_f32_e32 v162, v175, v175
	v_max_f32_e32 v162, v162, v0
	v_sub_f32_e32 v0, v175, v162
	v_exp_f32_e32 v0, v0
	v_mov_b32_e32 v175, v162
	v_mul_f32_e32 v174, v174, v0
	v_pk_mul_f32 v[32:33], v[32:33], v[0:1] op_sel_hi:[1,0]
	v_pk_mul_f32 v[30:31], v[30:31], v[0:1] op_sel_hi:[1,0]
	v_pk_mul_f32 v[28:29], v[28:29], v[0:1] op_sel_hi:[1,0]
	v_pk_mul_f32 v[26:27], v[26:27], v[0:1] op_sel_hi:[1,0]
	v_pk_mul_f32 v[24:25], v[24:25], v[0:1] op_sel_hi:[1,0]
	v_pk_mul_f32 v[22:23], v[22:23], v[0:1] op_sel_hi:[1,0]
	v_pk_mul_f32 v[20:21], v[20:21], v[0:1] op_sel_hi:[1,0]
	v_pk_mul_f32 v[18:19], v[18:19], v[0:1] op_sel_hi:[1,0]
	v_pk_mul_f32 v[16:17], v[16:17], v[0:1] op_sel_hi:[1,0]
	v_pk_mul_f32 v[14:15], v[14:15], v[0:1] op_sel_hi:[1,0]
	v_pk_mul_f32 v[12:13], v[12:13], v[0:1] op_sel_hi:[1,0]
	v_pk_mul_f32 v[10:11], v[10:11], v[0:1] op_sel_hi:[1,0]
	v_pk_mul_f32 v[8:9], v[8:9], v[0:1] op_sel_hi:[1,0]
	v_pk_mul_f32 v[6:7], v[6:7], v[0:1] op_sel_hi:[1,0]
	v_pk_mul_f32 v[4:5], v[4:5], v[0:1] op_sel_hi:[1,0]
	v_pk_mul_f32 v[2:3], v[2:3], v[0:1] op_sel_hi:[1,0]
	s_branch .LBB0_242

; __device__ __forceinline__ float fast_exp2(float x) { return __builtin_amdgcn_exp2f(x); }
; __device__ __forceinline__ void attn_block(KP p, LAS unsigned char* lds, int bh, int q0) {
;     ...
;             float mx = s0[0];
; #pragma unroll
;             for (int i = 1; i < 16; ++i) mx = fmaxf(mx, s0[i]);
; #pragma unroll
;             for (int i = 0; i < 16; ++i) mx = fmaxf(mx, s1[i]);
;             mx = fmaxf(mx, __shfl_xor(mx, 32));
;             if (__builtin_amdgcn_ballot_w64(mx > mrun) != 0ull) {
;                 const float mnew = fmaxf(mrun, mx), alpha = fast_exp2(mrun - mnew);
;                 lrun *= alpha; mrun = mnew; o0 = o0 * alpha; o1 = o1 * alpha;
;             }
.LBB0_267:
	s_nop 3
	v_max_f32_e32 v0, v51, v51
	v_max_f32_e32 v162, v50, v50
	v_max_f32_e32 v0, v162, v0
	v_max3_f32 v0, v0, v52, v53
	v_max3_f32 v0, v0, v54, v55
	v_max3_f32 v0, v0, v56, v57
	v_max3_f32 v0, v0, v58, v59
	v_max3_f32 v0, v0, v60, v61
	v_max3_f32 v0, v0, v62, v63
	v_max3_f32 v0, v0, v64, v65
	v_max3_f32 v0, v0, v34, v35
	v_max3_f32 v0, v0, v36, v37
	v_max3_f32 v0, v0, v38, v39
	v_max3_f32 v0, v0, v40, v41
	v_max3_f32 v0, v0, v42, v43
	v_max3_f32 v0, v0, v44, v45
	v_max3_f32 v0, v0, v46, v47
	v_max3_f32 v0, v0, v48, v49
	v_mov_b32_e32 v162, v0
	s_nop 1
	v_permlane32_swap_b32_e32 v162, v0
	s_waitcnt lgkmcnt(0)
	v_max_f32_e32 v0, v0, v162
	v_cmp_gt_f32_e32 vcc, v0, v176
	s_cbranch_vccz .LBB0_269
	v_max_f32_e32 v0, v0, v0
	v_max_f32_e32 v162, v176, v176
	v_max_f32_e32 v162, v162, v0
	v_sub_f32_e32 v0, v176, v162
	v_exp_f32_e32 v0, v0
	v_mov_b32_e32 v176, v162
	v_mul_f32_e32 v175, v175, v0
	v_pk_mul_f32 v[32:33], v[32:33], v[0:1] op_sel_hi:[1,0]
	v_pk_mul_f32 v[30:31], v[30:31], v[0:1] op_sel_hi:[1,0]
	v_pk_mul_f32 v[28:29], v[28:29], v[0:1] op_sel_hi:[1,0]
	v_pk_mul_f32 v[26:27], v[26:27], v[0:1] op_sel_hi:[1,0]
	v_pk_mul_f32 v[24:25], v[24:25], v[0:1] op_sel_hi:[1,0]
	v_pk_mul_f32 v[22:23], v[22:23], v[0:1] op_sel_hi:[1,0]
	v_pk_mul_f32 v[20:21], v[20:21], v[0:1] op_sel_hi:[1,0]
	v_pk_mul_f32 v[18:19], v[18:19], v[0:1] op_sel_hi:[1,0]
	v_pk_mul_f32 v[16:17], v[16:17], v[0:1] op_sel_hi:[1,0]
	v_pk_mul_f32 v[14:15], v[14:15], v[0:1] op_sel_hi:[1,0]
	v_pk_mul_f32 v[12:13], v[12:13], v[0:1] op_sel_hi:[1,0]
	v_pk_mul_f32 v[10:11], v[10:11], v[0:1] op_sel_hi:[1,0]
	v_pk_mul_f32 v[8:9], v[8:9], v[0:1] op_sel_hi:[1,0]
	v_pk_mul_f32 v[6:7], v[6:7], v[0:1] op_sel_hi:[1,0]
	v_pk_mul_f32 v[4:5], v[4:5], v[0:1] op_sel_hi:[1,0]
	v_pk_mul_f32 v[2:3], v[2:3], v[0:1] op_sel_hi:[1,0]

; __device__ __forceinline__ float fast_exp2(float x) { return __builtin_amdgcn_exp2f(x); }
; __device__ __forceinline__ void attn_block(KP p, LAS unsigned char* lds, int bh, int q0) {
;     ...
;             float mx = s0[0];
; #pragma unroll
;             for (int i = 1; i < 16; ++i) mx = fmaxf(mx, s0[i]);
; #pragma unroll
;             for (int i = 0; i < 16; ++i) mx = fmaxf(mx, s1[i]);
;             mx = fmaxf(mx, __shfl_xor(mx, 32));
;             if (__builtin_amdgcn_ballot_w64(mx > mrun) != 0ull) {
;                 const float mnew = fmaxf(mrun, mx), alpha = fast_exp2(mrun - mnew);
;                 lrun *= alpha; mrun = mnew; o0 = o0 * alpha; o1 = o1 * alpha;
;             }
.LBB0_273:
	s_nop 3
	v_max_f32_e32 v0, v51, v51
	v_max_f32_e32 v162, v50, v50
	v_max_f32_e32 v0, v162, v0
	v_max3_f32 v0, v0, v52, v53
	v_max3_f32 v0, v0, v54, v55
	v_max3_f32 v0, v0, v56, v57
	v_max3_f32 v0, v0, v58, v59
	v_max3_f32 v0, v0, v60, v61
	v_max3_f32 v0, v0, v62, v63
	v_max3_f32 v0, v0, v64, v65
	v_max3_f32 v0, v0, v34, v35
	v_max3_f32 v0, v0, v36, v37
	v_max3_f32 v0, v0, v38, v39
	v_max3_f32 v0, v0, v40, v41
	v_max3_f32 v0, v0, v42, v43
	v_max3_f32 v0, v0, v44, v45
	v_max3_f32 v0, v0, v46, v47
	v_max3_f32 v0, v0, v48, v49
	v_mov_b32_e32 v162, v0
	s_nop 1
	v_permlane32_swap_b32_e32 v162, v0
	s_waitcnt lgkmcnt(0)
	v_max_f32_e32 v0, v0, v162
	v_cmp_gt_f32_e32 vcc, v0, v176
	s_cbranch_vccz .LBB0_260
	v_max_f32_e32 v0, v0, v0
	v_max_f32_e32 v162, v176, v176
	v_max_f32_e32 v162, v162, v0
	v_sub_f32_e32 v0, v176, v162
	v_exp_f32_e32 v0, v0
	v_mov_b32_e32 v176, v162
	v_mul_f32_e32 v175, v175, v0
	v_pk_mul_f32 v[32:33], v[32:33], v[0:1] op_sel_hi:[1,0]
	v_pk_mul_f32 v[30:31], v[30:31], v[0:1] op_sel_hi:[1,0]
	v_pk_mul_f32 v[28:29], v[28:29], v[0:1] op_sel_hi:[1,0]
	v_pk_mul_f32 v[26:27], v[26:27], v[0:1] op_sel_hi:[1,0]
	v_pk_mul_f32 v[24:25], v[24:25], v[0:1] op_sel_hi:[1,0]
	v_pk_mul_f32 v[22:23], v[22:23], v[0:1] op_sel_hi:[1,0]
	v_pk_mul_f32 v[20:21], v[20:21], v[0:1] op_sel_hi:[1,0]
	v_pk_mul_f32 v[18:19], v[18:19], v[0:1] op_sel_hi:[1,0]
	v_pk_mul_f32 v[16:17], v[16:17], v[0:1] op_sel_hi:[1,0]
	v_pk_mul_f32 v[14:15], v[14:15], v[0:1] op_sel_hi:[1,0]
	v_pk_mul_f32 v[12:13], v[12:13], v[0:1] op_sel_hi:[1,0]
	v_pk_mul_f32 v[10:11], v[10:11], v[0:1] op_sel_hi:[1,0]
	v_pk_mul_f32 v[8:9], v[8:9], v[0:1] op_sel_hi:[1,0]
	v_pk_mul_f32 v[6:7], v[6:7], v[0:1] op_sel_hi:[1,0]
	v_pk_mul_f32 v[4:5], v[4:5], v[0:1] op_sel_hi:[1,0]
	v_pk_mul_f32 v[2:3], v[2:3], v[0:1] op_sel_hi:[1,0]
	s_branch .LBB0_260
